# v46 + E2 epilogue conv-branch columns staged through wave-private LDS and stored as 16-byte row chunks (was 8-byte pieces)
# speedup vs baseline: 1.0168x; 1.0168x over previous
.LBB0_880:
	s_or_saveexec_b64 s[2:3], s[2:3]
	v_ashrrev_i32_e32 v113, 31, v112
	v_lshlrev_b32_e32 v76, 1, v118
	s_xor_b64 exec, exec, s[2:3]
	s_cbranch_execz .LBB0_882
	s_movk_i32 s4, 0x90
	v_and_b32_e32 v240, 31, v155
	v_lshrrev_b32_e32 v239, 6, v155
	v_mul_u32_u24_e32 v239, 0x1400, v239
	v_mad_u32_u24 v238, v240, s4, v239
	v_add_u32_e32 v238, v238, v76
	v_bfe_u32 v246, v155, 3, 3
	v_sub_u32_e32 v247, v116, v240
	v_add_u32_e32 v247, v247, v246
	v_mad_u32_u24 v239, v246, s4, v239
	v_and_b32_e32 v246, 7, v155
	v_lshlrev_b32_e32 v246, 4, v246
	v_add_u32_e32 v239, v239, v246
	v_mov_b64_e32 v[72:73], s[58:59]
	s_movk_i32 s4, 0xc00
	v_mad_i64_i32 v[72:73], s[4:5], v247, s4, v[72:73]
	v_lshl_add_u64 v[72:73], v[112:113], 1, v[72:73]
	v_mov_b32_e32 v247, 0
	v_lshl_add_u64 v[72:73], v[72:73], 0, v[246:247]
	s_mov_b64 s[4:5], 0x6000
	v_cvt_pk_bf16_f32 v74, v104, v105
	v_cvt_pk_bf16_f32 v75, v106, v107
	ds_write_b64 v238, v[74:75]
	v_cvt_pk_bf16_f32 v74, v100, v101
	v_cvt_pk_bf16_f32 v75, v102, v103
	ds_write_b64 v238, v[74:75] offset:16
	v_cvt_pk_bf16_f32 v74, v96, v97
	v_cvt_pk_bf16_f32 v75, v98, v99
	ds_write_b64 v238, v[74:75] offset:32
	v_cvt_pk_bf16_f32 v74, v88, v89
	v_cvt_pk_bf16_f32 v75, v90, v91
	ds_write_b64 v238, v[74:75] offset:48
	v_cvt_pk_bf16_f32 v74, v84, v85
	v_cvt_pk_bf16_f32 v75, v86, v87
	ds_write_b64 v238, v[74:75] offset:64
	v_cvt_pk_bf16_f32 v74, v80, v81
	v_cvt_pk_bf16_f32 v75, v82, v83
	v_cvt_pk_bf16_f32 v68, v68, v69
	v_cvt_pk_bf16_f32 v69, v70, v71
	v_cvt_pk_bf16_f32 v64, v64, v65
	v_cvt_pk_bf16_f32 v65, v66, v67
	ds_write_b64 v238, v[74:75] offset:80
	ds_write_b64 v238, v[68:69] offset:96
	ds_write_b64 v238, v[64:65] offset:112
	s_waitcnt lgkmcnt(0)
	ds_read_b128 v[230:233], v239 offset:0
	ds_read_b128 v[234:237], v239 offset:1152
	ds_read_b128 v[182:185], v239 offset:2304
	ds_read_b128 v[186:189], v239 offset:3456
	s_waitcnt lgkmcnt(3)
	global_store_dwordx4 v[72:73], v[230:233], off
	v_lshl_add_u64 v[72:73], v[72:73], 0, s[4:5]
	s_waitcnt lgkmcnt(2)
	global_store_dwordx4 v[72:73], v[234:237], off
	v_lshl_add_u64 v[72:73], v[72:73], 0, s[4:5]
	s_waitcnt lgkmcnt(1)
	global_store_dwordx4 v[72:73], v[182:185], off
	v_lshl_add_u64 v[72:73], v[72:73], 0, s[4:5]
	s_waitcnt lgkmcnt(0)
	global_store_dwordx4 v[72:73], v[186:189], off

.LBB0_928:
	s_andn2_saveexec_b64 s[2:3], s[2:3]
	s_cbranch_execz .LBB0_930
	s_movk_i32 s4, 0x90
	v_and_b32_e32 v240, 31, v155
	v_lshrrev_b32_e32 v239, 6, v155
	v_mul_u32_u24_e32 v239, 0x1400, v239
	v_mad_u32_u24 v238, v240, s4, v239
	v_add_u32_e32 v238, v238, v76
	v_bfe_u32 v246, v155, 3, 3
	v_sub_u32_e32 v247, v78, v240
	v_add_u32_e32 v247, v247, v246
	v_mad_u32_u24 v239, v246, s4, v239
	v_and_b32_e32 v246, 7, v155
	v_lshlrev_b32_e32 v246, 4, v246
	v_add_u32_e32 v239, v239, v246
	v_mov_b64_e32 v[40:41], s[58:59]
	s_movk_i32 s4, 0xc00
	v_mad_i64_i32 v[40:41], s[4:5], v247, s4, v[40:41]
	v_lshl_add_u64 v[40:41], v[112:113], 1, v[40:41]
	v_mov_b32_e32 v247, 0
	v_lshl_add_u64 v[40:41], v[40:41], 0, v[246:247]
	s_mov_b64 s[4:5], 0x6000
	v_cvt_pk_bf16_f32 v42, v72, v73
	v_cvt_pk_bf16_f32 v43, v74, v75
	ds_write_b64 v238, v[42:43]
	v_cvt_pk_bf16_f32 v42, v68, v69
	v_cvt_pk_bf16_f32 v43, v70, v71
	ds_write_b64 v238, v[42:43] offset:16
	v_cvt_pk_bf16_f32 v42, v64, v65
	v_cvt_pk_bf16_f32 v43, v66, v67
	ds_write_b64 v238, v[42:43] offset:32
	v_cvt_pk_bf16_f32 v42, v56, v57
	v_cvt_pk_bf16_f32 v43, v58, v59
	ds_write_b64 v238, v[42:43] offset:48
	v_cvt_pk_bf16_f32 v42, v52, v53
	v_cvt_pk_bf16_f32 v43, v54, v55
	ds_write_b64 v238, v[42:43] offset:64
	v_cvt_pk_bf16_f32 v42, v48, v49
	v_cvt_pk_bf16_f32 v43, v50, v51
	v_cvt_pk_bf16_f32 v36, v36, v37
	v_cvt_pk_bf16_f32 v37, v38, v39
	v_cvt_pk_bf16_f32 v32, v32, v33
	v_cvt_pk_bf16_f32 v33, v34, v35
	ds_write_b64 v238, v[42:43] offset:80
	ds_write_b64 v238, v[36:37] offset:96
	ds_write_b64 v238, v[32:33] offset:112
	s_waitcnt lgkmcnt(0)
	ds_read_b128 v[230:233], v239 offset:0
	ds_read_b128 v[234:237], v239 offset:1152
	ds_read_b128 v[182:185], v239 offset:2304
	ds_read_b128 v[186:189], v239 offset:3456
	s_waitcnt lgkmcnt(3)
	global_store_dwordx4 v[40:41], v[230:233], off
	v_lshl_add_u64 v[40:41], v[40:41], 0, s[4:5]
	s_waitcnt lgkmcnt(2)
	global_store_dwordx4 v[40:41], v[234:237], off
	v_lshl_add_u64 v[40:41], v[40:41], 0, s[4:5]
	s_waitcnt lgkmcnt(1)
	global_store_dwordx4 v[40:41], v[182:185], off
	v_lshl_add_u64 v[40:41], v[40:41], 0, s[4:5]
	s_waitcnt lgkmcnt(0)
	global_store_dwordx4 v[40:41], v[186:189], off

.LBB0_977:
	s_movk_i32 s2, 0x90
	v_and_b32_e32 v240, 31, v155
	v_lshrrev_b32_e32 v239, 6, v155
	v_mul_u32_u24_e32 v239, 0x1400, v239
	v_mad_u32_u24 v238, v240, s2, v239
	v_add_u32_e32 v238, v238, v76
	v_bfe_u32 v246, v155, 3, 3
	v_sub_u32_e32 v247, v48, v240
	v_add_u32_e32 v247, v247, v246
	v_mad_u32_u24 v239, v246, s2, v239
	v_and_b32_e32 v246, 7, v155
	v_lshlrev_b32_e32 v246, 4, v246
	v_add_u32_e32 v239, v239, v246
	v_mov_b64_e32 v[16:17], s[58:59]
	s_movk_i32 s2, 0xc00
	v_mad_i64_i32 v[16:17], s[2:3], v247, s2, v[16:17]
	v_lshl_add_u64 v[16:17], v[112:113], 1, v[16:17]
	v_mov_b32_e32 v247, 0
	v_lshl_add_u64 v[16:17], v[16:17], 0, v[246:247]
	s_mov_b64 s[2:3], 0x6000
	v_cvt_pk_bf16_f32 v18, v44, v45
	v_cvt_pk_bf16_f32 v19, v46, v47
	ds_write_b64 v238, v[18:19]
	v_cvt_pk_bf16_f32 v18, v40, v41
	v_cvt_pk_bf16_f32 v19, v42, v43
	ds_write_b64 v238, v[18:19] offset:16
	v_cvt_pk_bf16_f32 v18, v36, v37
	v_cvt_pk_bf16_f32 v19, v38, v39
	ds_write_b64 v238, v[18:19] offset:32
	v_cvt_pk_bf16_f32 v18, v32, v33
	v_cvt_pk_bf16_f32 v19, v34, v35
	v_cvt_pk_bf16_f32 v12, v12, v13
	v_cvt_pk_bf16_f32 v13, v14, v15
	v_cvt_pk_bf16_f32 v8, v8, v9
	v_cvt_pk_bf16_f32 v9, v10, v11
	v_cvt_pk_bf16_f32 v4, v4, v5
	v_cvt_pk_bf16_f32 v5, v6, v7
	v_cvt_pk_bf16_f32 v0, v0, v1
	v_cvt_pk_bf16_f32 v1, v2, v3
	ds_write_b64 v238, v[18:19] offset:48
	ds_write_b64 v238, v[12:13] offset:64
	ds_write_b64 v238, v[8:9] offset:80
	ds_write_b64 v238, v[4:5] offset:96
	ds_write_b64 v238, v[0:1] offset:112
	s_waitcnt lgkmcnt(0)
	ds_read_b128 v[230:233], v239 offset:0
	ds_read_b128 v[234:237], v239 offset:1152
	ds_read_b128 v[182:185], v239 offset:2304
	ds_read_b128 v[186:189], v239 offset:3456
	s_waitcnt lgkmcnt(3)
	global_store_dwordx4 v[16:17], v[230:233], off
	v_lshl_add_u64 v[16:17], v[16:17], 0, s[2:3]
	s_waitcnt lgkmcnt(2)
	global_store_dwordx4 v[16:17], v[234:237], off
	v_lshl_add_u64 v[16:17], v[16:17], 0, s[2:3]
	s_waitcnt lgkmcnt(1)
	global_store_dwordx4 v[16:17], v[182:185], off
	v_lshl_add_u64 v[16:17], v[16:17], 0, s[2:3]
	s_waitcnt lgkmcnt(0)
	global_store_dwordx4 v[16:17], v[186:189], off
	s_branch .LBB0_829
